# ping-pong attention loop: row sums with v_pk_add_f32 (17 instead of 32 adds per 64-key step)
# baseline (speedup 1.0000x reference)
; #define MFMA(a, b, c) __builtin_amdgcn_mfma_f32_32x32x16_bf16((a), (b), (c), 0, 0, 0)
; DI float fexp2(float x) { return __builtin_amdgcn_exp2f(x); }
; DI void phase_attn(const Params& p, int hf, bool skipctx, char* smem, int& rot) {
;     ...
;       {
;         bf16x8 kf[2][6];
; #pragma unroll
;         for (int kb = 0; kb < 2; ++kb)
; #pragma unroll
;           for (int ks = 0; ks < 6; ++ks) kf[kb][ks] = *(const bf16x8*)(sk + (kb * 32 + r) * KROW + (ks * 16 + h * 8) * 2);
;         __builtin_amdgcn_sched_barrier(0);
; #pragma unroll
;         for (int ks = 0; ks < 6; ++ks)
; #pragma unroll
;           for (int kb = 0; kb < 2; ++kb) st[kb] = MFMA(kf[kb][ks], qf[ks], st[kb]);
;         __builtin_amdgcn_sched_barrier(0);
;       }
;       bf16x8 vf[2][2][2];
; #pragma unroll
;       for (int kb = 0; kb < 2; ++kb)
; #pragma unroll
;         for (int s2 = 0; s2 < 2; ++s2)
; #pragma unroll
;           for (int dvb = 0; dvb < 2; ++dvb) {
;             const char* vp = sv + (dvb * 32 + r) * VROW + (kb * 32 + 16 * s2 + 4 * h) * 2;
;             const s16x4 lo = *(const s16x4*)vp, hi = *(const s16x4*)(vp + 16);
;             vf[kb][s2][dvb] = __builtin_shufflevector(lo, hi, 0, 1, 2, 3, 4, 5, 6, 7);
;           }
;       float mx = st[0][0];
; #pragma unroll
;       for (int i = 0; i < 16; ++i) { mx = fmaxf(mx, st[0][i]); mx = fmaxf(mx, st[1][i]); }
;     ...
;       float ps = 0.f;
; #pragma unroll
;       for (int kb = 0; kb < 2; ++kb)
; #pragma unroll
;         for (int i = 0; i < 16; ++i) { const float e = fexp2(st[kb][i] - m_run); st[kb][i] = e; ps += e; }
;       l_run += ps;
.Lpq0_s0_n:
	v_exp_f32_e32 v48, v48
	v_exp_f32_e32 v49, v49
	v_exp_f32_e32 v50, v50
	v_exp_f32_e32 v51, v51
	v_exp_f32_e32 v52, v52
	v_exp_f32_e32 v53, v53
	v_exp_f32_e32 v54, v54
	v_exp_f32_e32 v55, v55
	v_exp_f32_e32 v56, v56
	v_exp_f32_e32 v57, v57
	v_exp_f32_e32 v58, v58
	v_exp_f32_e32 v59, v59
	v_exp_f32_e32 v60, v60
	v_exp_f32_e32 v61, v61
	v_exp_f32_e32 v62, v62
	v_exp_f32_e32 v63, v63
	v_pk_add_f32 v[200:201], v[48:49], v[50:51]
	v_pk_add_f32 v[200:201], v[200:201], v[52:53]
	v_pk_add_f32 v[200:201], v[200:201], v[54:55]
	v_pk_add_f32 v[200:201], v[200:201], v[56:57]
	v_pk_add_f32 v[200:201], v[200:201], v[58:59]
	v_pk_add_f32 v[200:201], v[200:201], v[60:61]
	v_pk_add_f32 v[200:201], v[200:201], v[62:63]
	v_cvt_pk_bf16_f32 v48, v48, v49
	v_cvt_pk_bf16_f32 v49, v50, v51
	v_cvt_pk_bf16_f32 v50, v52, v53
	v_cvt_pk_bf16_f32 v51, v54, v55
	v_cvt_pk_bf16_f32 v52, v56, v57
	v_cvt_pk_bf16_f32 v53, v58, v59
	v_cvt_pk_bf16_f32 v54, v60, v61
	v_cvt_pk_bf16_f32 v55, v62, v63
	v_exp_f32_e32 v32, v32
	v_exp_f32_e32 v33, v33
	v_exp_f32_e32 v34, v34
	v_exp_f32_e32 v35, v35
	v_exp_f32_e32 v36, v36
	v_exp_f32_e32 v37, v37
	v_exp_f32_e32 v38, v38
	v_exp_f32_e32 v39, v39
	v_exp_f32_e32 v40, v40
	v_exp_f32_e32 v41, v41
	v_exp_f32_e32 v42, v42
	v_exp_f32_e32 v43, v43
	v_exp_f32_e32 v44, v44
	v_exp_f32_e32 v45, v45
	v_exp_f32_e32 v46, v46
	v_exp_f32_e32 v47, v47
	v_pk_add_f32 v[200:201], v[200:201], v[32:33]
	v_pk_add_f32 v[200:201], v[200:201], v[34:35]
	v_pk_add_f32 v[200:201], v[200:201], v[36:37]
	v_pk_add_f32 v[200:201], v[200:201], v[38:39]
	v_pk_add_f32 v[200:201], v[200:201], v[40:41]
	v_pk_add_f32 v[200:201], v[200:201], v[42:43]
	v_pk_add_f32 v[200:201], v[200:201], v[44:45]
	v_pk_add_f32 v[200:201], v[200:201], v[46:47]
	v_cvt_pk_bf16_f32 v32, v32, v33
	v_cvt_pk_bf16_f32 v33, v34, v35
	v_cvt_pk_bf16_f32 v34, v36, v37
	v_cvt_pk_bf16_f32 v35, v38, v39
	v_cvt_pk_bf16_f32 v36, v40, v41
	v_cvt_pk_bf16_f32 v37, v42, v43
	v_cvt_pk_bf16_f32 v38, v44, v45
	v_cvt_pk_bf16_f32 v39, v46, v47
	v_add_f32_e32 v201, v200, v201
	v_add_f32_e32 v213, v213, v201
	ds_read_b128 v[214:217], v210 offset:13312
	ds_read_b128 v[234:237], v210 offset:13344
	ds_read_b128 v[238:241], v210 offset:13376
	ds_read_b128 v[242:245], v210 offset:13408
	ds_read_b128 v[40:43], v210 offset:13440
	ds_read_b128 v[44:47], v210 offset:13472
	s_waitcnt lgkmcnt(6)
	s_barrier
	s_waitcnt lgkmcnt(13)
	v_mfma_f32_32x32x16_bf16 v[16:31], v[128:131], v[48:51], v[16:31]
	ds_read_b128 v[128:131], v210 offset:19968
	s_waitcnt lgkmcnt(13)
	v_mfma_f32_32x32x16_bf16 v[0:15], v[132:135], v[48:51], v[0:15]
	ds_read_b128 v[132:135], v210 offset:20000
	s_waitcnt lgkmcnt(13)
	v_mfma_f32_32x32x16_bf16 v[16:31], v[136:139], v[52:55], v[16:31]
	ds_read_b128 v[136:139], v210 offset:20032
	s_waitcnt lgkmcnt(13)
	v_mfma_f32_32x32x16_bf16 v[0:15], v[140:143], v[52:55], v[0:15]
	ds_read_b128 v[140:143], v210 offset:20064
	s_waitcnt lgkmcnt(13)
	v_mfma_f32_32x32x16_bf16 v[16:31], v[144:147], v[32:35], v[16:31]
	ds_read_b128 v[144:147], v210 offset:20096
	s_waitcnt lgkmcnt(13)
	v_mfma_f32_32x32x16_bf16 v[0:15], v[148:151], v[32:35], v[0:15]
	ds_read_b128 v[148:151], v210 offset:20128
	s_waitcnt lgkmcnt(13)
	v_mfma_f32_32x32x16_bf16 v[16:31], v[152:155], v[36:39], v[16:31]
	s_waitcnt lgkmcnt(12)
	v_mfma_f32_32x32x16_bf16 v[0:15], v[156:159], v[36:39], v[0:15]
	s_waitcnt lgkmcnt(11)
	v_mfma_f32_32x32x16_bf16 v[48:63], v[214:217], v[64:67], v[176:191]
	s_waitcnt lgkmcnt(10)
	v_mfma_f32_32x32x16_bf16 v[48:63], v[234:237], v[68:71], v[48:63]
	s_waitcnt lgkmcnt(9)
	v_mfma_f32_32x32x16_bf16 v[48:63], v[238:241], v[72:75], v[48:63]
	s_waitcnt lgkmcnt(8)
	v_mfma_f32_32x32x16_bf16 v[48:63], v[242:245], v[88:91], v[48:63]
	s_waitcnt lgkmcnt(7)
	v_mfma_f32_32x32x16_bf16 v[48:63], v[40:43], v[96:99], v[48:63]
	s_waitcnt lgkmcnt(6)
	v_mfma_f32_32x32x16_bf16 v[48:63], v[44:47], v[100:103], v[48:63]
	s_waitcnt lgkmcnt(5)
	v_mfma_f32_32x32x16_bf16 v[32:47], v[128:131], v[64:67], v[176:191]
	s_waitcnt lgkmcnt(4)
	v_mfma_f32_32x32x16_bf16 v[32:47], v[132:135], v[68:71], v[32:47]
	s_waitcnt lgkmcnt(3)
	v_mfma_f32_32x32x16_bf16 v[32:47], v[136:139], v[72:75], v[32:47]
	s_waitcnt lgkmcnt(2)
	v_mfma_f32_32x32x16_bf16 v[32:47], v[140:143], v[88:91], v[32:47]
	s_waitcnt lgkmcnt(1)
	v_mfma_f32_32x32x16_bf16 v[32:47], v[144:147], v[96:99], v[32:47]
	s_waitcnt lgkmcnt(0)
	v_mfma_f32_32x32x16_bf16 v[32:47], v[148:151], v[100:103], v[32:47]
	s_barrier
	ds_read_b128 v[128:131], v211 offset:128
	ds_read_b128 v[132:135], v211 offset:8832
	ds_read_b128 v[136:139], v211 offset:160
	ds_read_b128 v[140:143], v211 offset:8864
	ds_read_b128 v[144:147], v211 offset:192
	ds_read_b128 v[148:151], v211 offset:8896
	ds_read_b128 v[152:155], v211 offset:224
	ds_read_b128 v[156:159], v211 offset:8928
	s_nop 3
	v_max3_f32 v195, v48, v49, v50
	v_max3_f32 v200, v32, v33, v34
	v_max3_f32 v195, v195, v51, v52
	v_max3_f32 v200, v200, v35, v36
	v_max3_f32 v195, v195, v53, v54
	v_max3_f32 v200, v200, v37, v38
	v_max3_f32 v195, v195, v55, v56
	v_max3_f32 v200, v200, v39, v40
	v_max3_f32 v195, v195, v57, v58
	v_max3_f32 v200, v200, v41, v42
	v_max3_f32 v195, v195, v59, v60
	v_max3_f32 v200, v200, v43, v44
	v_max3_f32 v195, v195, v61, v62
	v_max3_f32 v200, v200, v45, v46
	v_max3_f32 v195, v195, v63, v47
	v_max_f32_e32 v195, v195, v200
	v_cmp_gt_f32_e32 vcc, v195, v220
	s_cbranch_vccz .Lpq0_s1_n
; DI float fexp2(float x) { return __builtin_amdgcn_exp2f(x); }
; DI void phase_attn(const Params& p, int hf, bool skipctx, char* smem, int& rot) {
;     ...
;       if (__any(mx > m_run + 8.f)) {
;         mx = fmaxf(mx, __shfl_xor(mx, 32));
;         const float m_new = fmaxf(m_run, mx);
;         const float alpha = fexp2(m_run - m_new);
;         m_run = m_new;
;         l_run *= alpha;
; #pragma unroll
;         for (int i = 0; i < 16; ++i) { o[0][i] *= alpha; o[1][i] *= alpha; }
;       }
;       float ps = 0.f;
; #pragma unroll
;       for (int kb = 0; kb < 2; ++kb)
; #pragma unroll
;         for (int i = 0; i < 16; ++i) { const float e = fexp2(st[kb][i] - m_run); st[kb][i] = e; ps += e; }
;       l_run += ps;
; #pragma unroll
;       for (int kb = 0; kb < 2; ++kb)
; #pragma unroll
;         for (int s2 = 0; s2 < 2; ++s2) {
;           const bf16x8 pb = pack8(st[kb][8 * s2 + 0], st[kb][8 * s2 + 1], st[kb][8 * s2 + 2], st[kb][8 * s2 + 3], st[kb][8 * s2 + 4], st[kb][8 * s2 + 5], st[kb][8 * s2 + 6], st[kb][8 * s2 + 7]);
;     ...
;       if (kt + 3 < nkt) ATT_LOAD(bk0, bk1, bk2, bv0, bv1, kt + 3);
	v_sub_f32_e32 v195, v195, v176
	v_cmp_lt_i32_e32 vcc, v224, v207
	s_nop 1
	v_cndmask_b32_e32 v200, v205, v224, vcc
	v_lshlrev_b32_e32 v200, 2, v200
	ds_bpermute_b32 v200, v200, v195
	s_waitcnt lgkmcnt(0)
	v_max3_f32 v195, v212, v195, v200
	v_sub_f32_e32 v200, v212, v195
	v_exp_f32_e32 v200, v200
	v_mov_b32_e32 v212, v195
	v_add_f32_e32 v202, v195, v176
	v_mul_f32_e32 v213, v213, v200
	v_pk_mul_f32 v[30:31], v[30:31], v[200:201] op_sel_hi:[1,0]
	v_pk_mul_f32 v[28:29], v[28:29], v[200:201] op_sel_hi:[1,0]
	v_pk_mul_f32 v[26:27], v[26:27], v[200:201] op_sel_hi:[1,0]
	v_pk_mul_f32 v[24:25], v[24:25], v[200:201] op_sel_hi:[1,0]
	v_pk_mul_f32 v[22:23], v[22:23], v[200:201] op_sel_hi:[1,0]
	v_pk_mul_f32 v[20:21], v[20:21], v[200:201] op_sel_hi:[1,0]
	v_pk_mul_f32 v[18:19], v[18:19], v[200:201] op_sel_hi:[1,0]
	v_pk_mul_f32 v[16:17], v[16:17], v[200:201] op_sel_hi:[1,0]
	v_pk_mul_f32 v[14:15], v[14:15], v[200:201] op_sel_hi:[1,0]
	v_pk_mul_f32 v[12:13], v[12:13], v[200:201] op_sel_hi:[1,0]
	v_pk_mul_f32 v[10:11], v[10:11], v[200:201] op_sel_hi:[1,0]
	v_pk_mul_f32 v[8:9], v[8:9], v[200:201] op_sel_hi:[1,0]
	v_pk_mul_f32 v[6:7], v[6:7], v[200:201] op_sel_hi:[1,0]
	v_pk_mul_f32 v[4:5], v[4:5], v[200:201] op_sel_hi:[1,0]
	v_pk_mul_f32 v[2:3], v[2:3], v[200:201] op_sel_hi:[1,0]
	v_pk_mul_f32 v[0:1], v[0:1], v[200:201] op_sel_hi:[1,0]
	v_sub_f32_e32 v32, v32, v202
	v_sub_f32_e32 v33, v33, v202
	v_sub_f32_e32 v34, v34, v202
	v_sub_f32_e32 v35, v35, v202
	v_sub_f32_e32 v36, v36, v202
	v_sub_f32_e32 v37, v37, v202
	v_sub_f32_e32 v38, v38, v202
	v_sub_f32_e32 v39, v39, v202
	v_sub_f32_e32 v40, v40, v202
	v_sub_f32_e32 v41, v41, v202
	v_sub_f32_e32 v42, v42, v202
	v_sub_f32_e32 v43, v43, v202
	v_sub_f32_e32 v44, v44, v202
	v_sub_f32_e32 v45, v45, v202
	v_sub_f32_e32 v46, v46, v202
	v_sub_f32_e32 v47, v47, v202
	v_sub_f32_e32 v48, v48, v202
	v_sub_f32_e32 v49, v49, v202
	v_sub_f32_e32 v50, v50, v202
	v_sub_f32_e32 v51, v51, v202
	v_sub_f32_e32 v52, v52, v202
	v_sub_f32_e32 v53, v53, v202
	v_sub_f32_e32 v54, v54, v202
	v_sub_f32_e32 v55, v55, v202
	v_sub_f32_e32 v56, v56, v202
	v_sub_f32_e32 v57, v57, v202
	v_sub_f32_e32 v58, v58, v202
	v_sub_f32_e32 v59, v59, v202
	v_sub_f32_e32 v60, v60, v202
	v_sub_f32_e32 v61, v61, v202
	v_sub_f32_e32 v62, v62, v202
	v_sub_f32_e32 v63, v63, v202
	v_sub_f32_e32 v176, 0, v195
	v_sub_f32_e32 v177, 0, v195
	v_sub_f32_e32 v178, 0, v195
	v_sub_f32_e32 v179, 0, v195
	v_sub_f32_e32 v180, 0, v195
	v_sub_f32_e32 v181, 0, v195
	v_sub_f32_e32 v182, 0, v195
	v_sub_f32_e32 v183, 0, v195
	v_sub_f32_e32 v184, 0, v195
	v_sub_f32_e32 v185, 0, v195
	v_sub_f32_e32 v186, 0, v195
	v_sub_f32_e32 v187, 0, v195
	v_sub_f32_e32 v188, 0, v195
	v_sub_f32_e32 v189, 0, v195
	v_sub_f32_e32 v190, 0, v195
	v_sub_f32_e32 v191, 0, v195
	v_mov_b32_e32 v220, 0x41000000
.Lpq0_s1_n:
	v_exp_f32_e32 v48, v48
	v_exp_f32_e32 v49, v49
	v_exp_f32_e32 v50, v50
	v_exp_f32_e32 v51, v51
	v_exp_f32_e32 v52, v52
	v_exp_f32_e32 v53, v53
	v_exp_f32_e32 v54, v54
	v_exp_f32_e32 v55, v55
	v_exp_f32_e32 v56, v56
	v_exp_f32_e32 v57, v57
	v_exp_f32_e32 v58, v58
	v_exp_f32_e32 v59, v59
	v_exp_f32_e32 v60, v60
	v_exp_f32_e32 v61, v61
	v_exp_f32_e32 v62, v62
	v_exp_f32_e32 v63, v63
	v_pk_add_f32 v[200:201], v[48:49], v[50:51]
	v_pk_add_f32 v[200:201], v[200:201], v[52:53]
	v_pk_add_f32 v[200:201], v[200:201], v[54:55]
	v_pk_add_f32 v[200:201], v[200:201], v[56:57]
	v_pk_add_f32 v[200:201], v[200:201], v[58:59]
	v_pk_add_f32 v[200:201], v[200:201], v[60:61]
	v_pk_add_f32 v[200:201], v[200:201], v[62:63]
	v_cvt_pk_bf16_f32 v48, v48, v49
	v_cvt_pk_bf16_f32 v49, v50, v51
	v_cvt_pk_bf16_f32 v50, v52, v53
	v_cvt_pk_bf16_f32 v51, v54, v55
	v_cvt_pk_bf16_f32 v52, v56, v57
	v_cvt_pk_bf16_f32 v53, v58, v59
	v_cvt_pk_bf16_f32 v54, v60, v61
	v_cvt_pk_bf16_f32 v55, v62, v63
	v_exp_f32_e32 v32, v32
	v_exp_f32_e32 v33, v33
	v_exp_f32_e32 v34, v34
	v_exp_f32_e32 v35, v35
	v_exp_f32_e32 v36, v36
	v_exp_f32_e32 v37, v37
	v_exp_f32_e32 v38, v38
	v_exp_f32_e32 v39, v39
	v_exp_f32_e32 v40, v40
	v_exp_f32_e32 v41, v41
	v_exp_f32_e32 v42, v42
	v_exp_f32_e32 v43, v43
	v_exp_f32_e32 v44, v44
	v_exp_f32_e32 v45, v45
	v_exp_f32_e32 v46, v46
	v_exp_f32_e32 v47, v47
	v_pk_add_f32 v[200:201], v[200:201], v[32:33]
	v_pk_add_f32 v[200:201], v[200:201], v[34:35]
	v_pk_add_f32 v[200:201], v[200:201], v[36:37]
	v_pk_add_f32 v[200:201], v[200:201], v[38:39]
	v_pk_add_f32 v[200:201], v[200:201], v[40:41]
	v_pk_add_f32 v[200:201], v[200:201], v[42:43]
	v_pk_add_f32 v[200:201], v[200:201], v[44:45]
	v_pk_add_f32 v[200:201], v[200:201], v[46:47]
	v_cvt_pk_bf16_f32 v32, v32, v33
	v_cvt_pk_bf16_f32 v33, v34, v35
	v_cvt_pk_bf16_f32 v34, v36, v37
	v_cvt_pk_bf16_f32 v35, v38, v39
	v_cvt_pk_bf16_f32 v36, v40, v41
	v_cvt_pk_bf16_f32 v37, v42, v43
	v_cvt_pk_bf16_f32 v38, v44, v45
	v_cvt_pk_bf16_f32 v39, v46, v47
	v_add_f32_e32 v201, v200, v201
	v_add_f32_e32 v213, v213, v201
	ds_read_b128 v[214:217], v210 offset:44032
	ds_read_b128 v[234:237], v210 offset:44064
	ds_read_b128 v[238:241], v210 offset:44096
	ds_read_b128 v[242:245], v210 offset:44128
	ds_read_b128 v[40:43], v210 offset:44160
	ds_read_b128 v[44:47], v210 offset:44192
	s_barrier
	s_add_i32 s4, s4, 3
	s_cmp_ge_u32 s4, s13
	s_cbranch_scc1 .Lpq0_lb
	v_lshl_add_u64 v[108:109], s[94:95], 0, v[174:175]
	v_add_co_u32_e32 v108, vcc, 0x18b2e000, v108
	v_lshl_add_u64 v[110:111], s[94:95], 0, v[172:173]
	s_nop 0
	v_addc_co_u32_e32 v109, vcc, 0, v109, vcc
	v_add_co_u32_e32 v110, vcc, 0x18b2e000, v110
	v_lshl_add_u64 v[116:117], s[94:95], 0, v[170:171]
	s_nop 0
	v_addc_co_u32_e32 v111, vcc, 0, v111, vcc
	v_add_co_u32_e32 v116, vcc, 0x18b2e000, v116
	v_lshl_add_u64 v[120:121], s[94:95], 0, v[166:167]
	s_nop 0
	v_addc_co_u32_e32 v117, vcc, 0, v117, vcc
	v_lshl_add_u64 v[124:125], s[94:95], 0, v[168:169]
	global_load_dwordx4 v[112:115], v[108:109], off
	s_nop 0
	global_load_dwordx4 v[108:111], v[110:111], off
	s_nop 0
	global_load_dwordx4 v[116:119], v[116:117], off
	s_nop 0
	global_load_dwordx4 v[120:123], v[120:121], off
	s_nop 0
	global_load_dwordx4 v[124:127], v[124:125], off

; #define MFMA(a, b, c) __builtin_amdgcn_mfma_f32_32x32x16_bf16((a), (b), (c), 0, 0, 0)
; DI float fexp2(float x) { return __builtin_amdgcn_exp2f(x); }
; DI void phase_attn(const Params& p, int hf, bool skipctx, char* smem, int& rot) {
;     ...
;       {
;         bf16x8 kf[2][6];
; #pragma unroll
;         for (int kb = 0; kb < 2; ++kb)
; #pragma unroll
;           for (int ks = 0; ks < 6; ++ks) kf[kb][ks] = *(const bf16x8*)(sk + (kb * 32 + r) * KROW + (ks * 16 + h * 8) * 2);
;         __builtin_amdgcn_sched_barrier(0);
; #pragma unroll
;         for (int ks = 0; ks < 6; ++ks)
; #pragma unroll
;           for (int kb = 0; kb < 2; ++kb) st[kb] = MFMA(kf[kb][ks], qf[ks], st[kb]);
;         __builtin_amdgcn_sched_barrier(0);
;       }
;       bf16x8 vf[2][2][2];
; #pragma unroll
;       for (int kb = 0; kb < 2; ++kb)
; #pragma unroll
;         for (int s2 = 0; s2 < 2; ++s2)
; #pragma unroll
;           for (int dvb = 0; dvb < 2; ++dvb) {
;             const char* vp = sv + (dvb * 32 + r) * VROW + (kb * 32 + 16 * s2 + 4 * h) * 2;
;             const s16x4 lo = *(const s16x4*)vp, hi = *(const s16x4*)(vp + 16);
;             vf[kb][s2][dvb] = __builtin_shufflevector(lo, hi, 0, 1, 2, 3, 4, 5, 6, 7);
;           }
;       float mx = st[0][0];
; #pragma unroll
;       for (int i = 0; i < 16; ++i) { mx = fmaxf(mx, st[0][i]); mx = fmaxf(mx, st[1][i]); }
;     ...
;       float ps = 0.f;
; #pragma unroll
;       for (int kb = 0; kb < 2; ++kb)
; #pragma unroll
;         for (int i = 0; i < 16; ++i) { const float e = fexp2(st[kb][i] - m_run); st[kb][i] = e; ps += e; }
;       l_run += ps;
.Lpq0_s2_n:
	v_exp_f32_e32 v48, v48
	v_exp_f32_e32 v49, v49
	v_exp_f32_e32 v50, v50
	v_exp_f32_e32 v51, v51
	v_exp_f32_e32 v52, v52
	v_exp_f32_e32 v53, v53
	v_exp_f32_e32 v54, v54
	v_exp_f32_e32 v55, v55
	v_exp_f32_e32 v56, v56
	v_exp_f32_e32 v57, v57
	v_exp_f32_e32 v58, v58
	v_exp_f32_e32 v59, v59
	v_exp_f32_e32 v60, v60
	v_exp_f32_e32 v61, v61
	v_exp_f32_e32 v62, v62
	v_exp_f32_e32 v63, v63
	v_pk_add_f32 v[200:201], v[48:49], v[50:51]
	v_pk_add_f32 v[200:201], v[200:201], v[52:53]
	v_pk_add_f32 v[200:201], v[200:201], v[54:55]
	v_pk_add_f32 v[200:201], v[200:201], v[56:57]
	v_pk_add_f32 v[200:201], v[200:201], v[58:59]
	v_pk_add_f32 v[200:201], v[200:201], v[60:61]
	v_pk_add_f32 v[200:201], v[200:201], v[62:63]
	v_cvt_pk_bf16_f32 v48, v48, v49
	v_cvt_pk_bf16_f32 v49, v50, v51
	v_cvt_pk_bf16_f32 v50, v52, v53
	v_cvt_pk_bf16_f32 v51, v54, v55
	v_cvt_pk_bf16_f32 v52, v56, v57
	v_cvt_pk_bf16_f32 v53, v58, v59
	v_cvt_pk_bf16_f32 v54, v60, v61
	v_cvt_pk_bf16_f32 v55, v62, v63
	v_exp_f32_e32 v32, v32
	v_exp_f32_e32 v33, v33
	v_exp_f32_e32 v34, v34
	v_exp_f32_e32 v35, v35
	v_exp_f32_e32 v36, v36
	v_exp_f32_e32 v37, v37
	v_exp_f32_e32 v38, v38
	v_exp_f32_e32 v39, v39
	v_exp_f32_e32 v40, v40
	v_exp_f32_e32 v41, v41
	v_exp_f32_e32 v42, v42
	v_exp_f32_e32 v43, v43
	v_exp_f32_e32 v44, v44
	v_exp_f32_e32 v45, v45
	v_exp_f32_e32 v46, v46
	v_exp_f32_e32 v47, v47
	v_pk_add_f32 v[200:201], v[200:201], v[32:33]
	v_pk_add_f32 v[200:201], v[200:201], v[34:35]
	v_pk_add_f32 v[200:201], v[200:201], v[36:37]
	v_pk_add_f32 v[200:201], v[200:201], v[38:39]
	v_pk_add_f32 v[200:201], v[200:201], v[40:41]
	v_pk_add_f32 v[200:201], v[200:201], v[42:43]
	v_pk_add_f32 v[200:201], v[200:201], v[44:45]
	v_pk_add_f32 v[200:201], v[200:201], v[46:47]
	v_cvt_pk_bf16_f32 v32, v32, v33
	v_cvt_pk_bf16_f32 v33, v34, v35
	v_cvt_pk_bf16_f32 v34, v36, v37
	v_cvt_pk_bf16_f32 v35, v38, v39
	v_cvt_pk_bf16_f32 v36, v40, v41
	v_cvt_pk_bf16_f32 v37, v42, v43
	v_cvt_pk_bf16_f32 v38, v44, v45
	v_cvt_pk_bf16_f32 v39, v46, v47
	v_add_f32_e32 v201, v200, v201
	v_add_f32_e32 v213, v213, v201
	ds_read_b128 v[214:217], v210 offset:57344
	ds_read_b128 v[234:237], v210 offset:57376
	ds_read_b128 v[238:241], v210 offset:57408
	ds_read_b128 v[242:245], v210 offset:57440
	ds_read_b128 v[40:43], v210 offset:57472
	ds_read_b128 v[44:47], v210 offset:57504
	s_waitcnt lgkmcnt(6)
	s_barrier
	s_waitcnt lgkmcnt(13)
	v_mfma_f32_32x32x16_bf16 v[16:31], v[128:131], v[48:51], v[16:31]
	ds_read_b128 v[128:131], v210 offset:64000
	s_waitcnt lgkmcnt(13)
	v_mfma_f32_32x32x16_bf16 v[0:15], v[132:135], v[48:51], v[0:15]
	ds_read_b128 v[132:135], v210 offset:64032
	s_waitcnt lgkmcnt(13)
	v_mfma_f32_32x32x16_bf16 v[16:31], v[136:139], v[52:55], v[16:31]
	ds_read_b128 v[136:139], v210 offset:64064
	s_waitcnt lgkmcnt(13)
	v_mfma_f32_32x32x16_bf16 v[0:15], v[140:143], v[52:55], v[0:15]
	ds_read_b128 v[140:143], v210 offset:64096
	s_waitcnt lgkmcnt(13)
	v_mfma_f32_32x32x16_bf16 v[16:31], v[144:147], v[32:35], v[16:31]
	ds_read_b128 v[144:147], v210 offset:64128
	s_waitcnt lgkmcnt(13)
	v_mfma_f32_32x32x16_bf16 v[0:15], v[148:151], v[32:35], v[0:15]
	ds_read_b128 v[148:151], v210 offset:64160
	s_waitcnt lgkmcnt(13)
	v_mfma_f32_32x32x16_bf16 v[16:31], v[152:155], v[36:39], v[16:31]
	s_waitcnt lgkmcnt(12)
	v_mfma_f32_32x32x16_bf16 v[0:15], v[156:159], v[36:39], v[0:15]
	s_waitcnt lgkmcnt(11)
	v_mfma_f32_32x32x16_bf16 v[48:63], v[214:217], v[64:67], v[176:191]
	s_waitcnt lgkmcnt(10)
	v_mfma_f32_32x32x16_bf16 v[48:63], v[234:237], v[68:71], v[48:63]
	s_waitcnt lgkmcnt(9)
	v_mfma_f32_32x32x16_bf16 v[48:63], v[238:241], v[72:75], v[48:63]
	s_waitcnt lgkmcnt(8)
	v_mfma_f32_32x32x16_bf16 v[48:63], v[242:245], v[88:91], v[48:63]
	s_waitcnt lgkmcnt(7)
	v_mfma_f32_32x32x16_bf16 v[48:63], v[40:43], v[96:99], v[48:63]
	s_waitcnt lgkmcnt(6)
	v_mfma_f32_32x32x16_bf16 v[48:63], v[44:47], v[100:103], v[48:63]
	s_waitcnt lgkmcnt(5)
	v_mfma_f32_32x32x16_bf16 v[32:47], v[128:131], v[64:67], v[176:191]
	s_waitcnt lgkmcnt(4)
	v_mfma_f32_32x32x16_bf16 v[32:47], v[132:135], v[68:71], v[32:47]
	s_waitcnt lgkmcnt(3)
	v_mfma_f32_32x32x16_bf16 v[32:47], v[136:139], v[72:75], v[32:47]
	s_waitcnt lgkmcnt(2)
	v_mfma_f32_32x32x16_bf16 v[32:47], v[140:143], v[88:91], v[32:47]
	s_waitcnt lgkmcnt(1)
	v_mfma_f32_32x32x16_bf16 v[32:47], v[144:147], v[96:99], v[32:47]
	s_waitcnt lgkmcnt(0)
	v_mfma_f32_32x32x16_bf16 v[32:47], v[148:151], v[100:103], v[32:47]
	s_barrier
	ds_read_b128 v[128:131], v211 offset:44160
	ds_read_b128 v[132:135], v211 offset:52864
	ds_read_b128 v[136:139], v211 offset:44192
	ds_read_b128 v[140:143], v211 offset:52896
	ds_read_b128 v[144:147], v211 offset:44224
	ds_read_b128 v[148:151], v211 offset:52928
	ds_read_b128 v[152:155], v211 offset:44256
	ds_read_b128 v[156:159], v211 offset:52960
	s_nop 3
	v_max3_f32 v195, v48, v49, v50
	v_max3_f32 v200, v32, v33, v34
	v_max3_f32 v195, v195, v51, v52
	v_max3_f32 v200, v200, v35, v36
	v_max3_f32 v195, v195, v53, v54
	v_max3_f32 v200, v200, v37, v38
	v_max3_f32 v195, v195, v55, v56
	v_max3_f32 v200, v200, v39, v40
	v_max3_f32 v195, v195, v57, v58
	v_max3_f32 v200, v200, v41, v42
	v_max3_f32 v195, v195, v59, v60
	v_max3_f32 v200, v200, v43, v44
	v_max3_f32 v195, v195, v61, v62
	v_max3_f32 v200, v200, v45, v46
	v_max3_f32 v195, v195, v63, v47
	v_max_f32_e32 v195, v195, v200
	v_cmp_gt_f32_e32 vcc, v195, v220
	s_cbranch_vccz .Lpq0_s3_n
; DI float fexp2(float x) { return __builtin_amdgcn_exp2f(x); }
; DI void phase_attn(const Params& p, int hf, bool skipctx, char* smem, int& rot) {
;     ...
;       if (__any(mx > m_run + 8.f)) {
;         mx = fmaxf(mx, __shfl_xor(mx, 32));
;         const float m_new = fmaxf(m_run, mx);
;         const float alpha = fexp2(m_run - m_new);
;         m_run = m_new;
;         l_run *= alpha;
; #pragma unroll
;         for (int i = 0; i < 16; ++i) { o[0][i] *= alpha; o[1][i] *= alpha; }
;       }
;       float ps = 0.f;
; #pragma unroll
;       for (int kb = 0; kb < 2; ++kb)
; #pragma unroll
;         for (int i = 0; i < 16; ++i) { const float e = fexp2(st[kb][i] - m_run); st[kb][i] = e; ps += e; }
;       l_run += ps;
; #pragma unroll
;       for (int kb = 0; kb < 2; ++kb)
; #pragma unroll
;         for (int s2 = 0; s2 < 2; ++s2) {
;           const bf16x8 pb = pack8(st[kb][8 * s2 + 0], st[kb][8 * s2 + 1], st[kb][8 * s2 + 2], st[kb][8 * s2 + 3], st[kb][8 * s2 + 4], st[kb][8 * s2 + 5], st[kb][8 * s2 + 6], st[kb][8 * s2 + 7]);
;     ...
;     for (int kt = 0; kt < nkt; kt += 2) {
	v_sub_f32_e32 v195, v195, v176
	v_cmp_lt_i32_e32 vcc, v224, v207
	s_nop 1
	v_cndmask_b32_e32 v200, v205, v224, vcc
	v_lshlrev_b32_e32 v200, 2, v200
	ds_bpermute_b32 v200, v200, v195
	s_waitcnt lgkmcnt(0)
	v_max3_f32 v195, v212, v195, v200
	v_sub_f32_e32 v200, v212, v195
	v_exp_f32_e32 v200, v200
	v_mov_b32_e32 v212, v195
	v_add_f32_e32 v202, v195, v176
	v_mul_f32_e32 v213, v213, v200
	v_pk_mul_f32 v[30:31], v[30:31], v[200:201] op_sel_hi:[1,0]
	v_pk_mul_f32 v[28:29], v[28:29], v[200:201] op_sel_hi:[1,0]
	v_pk_mul_f32 v[26:27], v[26:27], v[200:201] op_sel_hi:[1,0]
	v_pk_mul_f32 v[24:25], v[24:25], v[200:201] op_sel_hi:[1,0]
	v_pk_mul_f32 v[22:23], v[22:23], v[200:201] op_sel_hi:[1,0]
	v_pk_mul_f32 v[20:21], v[20:21], v[200:201] op_sel_hi:[1,0]
	v_pk_mul_f32 v[18:19], v[18:19], v[200:201] op_sel_hi:[1,0]
	v_pk_mul_f32 v[16:17], v[16:17], v[200:201] op_sel_hi:[1,0]
	v_pk_mul_f32 v[14:15], v[14:15], v[200:201] op_sel_hi:[1,0]
	v_pk_mul_f32 v[12:13], v[12:13], v[200:201] op_sel_hi:[1,0]
	v_pk_mul_f32 v[10:11], v[10:11], v[200:201] op_sel_hi:[1,0]
	v_pk_mul_f32 v[8:9], v[8:9], v[200:201] op_sel_hi:[1,0]
	v_pk_mul_f32 v[6:7], v[6:7], v[200:201] op_sel_hi:[1,0]
	v_pk_mul_f32 v[4:5], v[4:5], v[200:201] op_sel_hi:[1,0]
	v_pk_mul_f32 v[2:3], v[2:3], v[200:201] op_sel_hi:[1,0]
	v_pk_mul_f32 v[0:1], v[0:1], v[200:201] op_sel_hi:[1,0]
	v_sub_f32_e32 v32, v32, v202
	v_sub_f32_e32 v33, v33, v202
	v_sub_f32_e32 v34, v34, v202
	v_sub_f32_e32 v35, v35, v202
	v_sub_f32_e32 v36, v36, v202
	v_sub_f32_e32 v37, v37, v202
	v_sub_f32_e32 v38, v38, v202
	v_sub_f32_e32 v39, v39, v202
	v_sub_f32_e32 v40, v40, v202
	v_sub_f32_e32 v41, v41, v202
	v_sub_f32_e32 v42, v42, v202
	v_sub_f32_e32 v43, v43, v202
	v_sub_f32_e32 v44, v44, v202
	v_sub_f32_e32 v45, v45, v202
	v_sub_f32_e32 v46, v46, v202
	v_sub_f32_e32 v47, v47, v202
	v_sub_f32_e32 v48, v48, v202
	v_sub_f32_e32 v49, v49, v202
	v_sub_f32_e32 v50, v50, v202
	v_sub_f32_e32 v51, v51, v202
	v_sub_f32_e32 v52, v52, v202
	v_sub_f32_e32 v53, v53, v202
	v_sub_f32_e32 v54, v54, v202
	v_sub_f32_e32 v55, v55, v202
	v_sub_f32_e32 v56, v56, v202
	v_sub_f32_e32 v57, v57, v202
	v_sub_f32_e32 v58, v58, v202
	v_sub_f32_e32 v59, v59, v202
	v_sub_f32_e32 v60, v60, v202
	v_sub_f32_e32 v61, v61, v202
	v_sub_f32_e32 v62, v62, v202
	v_sub_f32_e32 v63, v63, v202
	v_sub_f32_e32 v176, 0, v195
	v_sub_f32_e32 v177, 0, v195
	v_sub_f32_e32 v178, 0, v195
	v_sub_f32_e32 v179, 0, v195
	v_sub_f32_e32 v180, 0, v195
	v_sub_f32_e32 v181, 0, v195
	v_sub_f32_e32 v182, 0, v195
	v_sub_f32_e32 v183, 0, v195
	v_sub_f32_e32 v184, 0, v195
	v_sub_f32_e32 v185, 0, v195
	v_sub_f32_e32 v186, 0, v195
	v_sub_f32_e32 v187, 0, v195
	v_sub_f32_e32 v188, 0, v195
	v_sub_f32_e32 v189, 0, v195
	v_sub_f32_e32 v190, 0, v195
	v_sub_f32_e32 v191, 0, v195
	v_mov_b32_e32 v220, 0x41000000
.Lpq0_s3_n:
	v_exp_f32_e32 v48, v48
	v_exp_f32_e32 v49, v49
	v_exp_f32_e32 v50, v50
	v_exp_f32_e32 v51, v51
	v_exp_f32_e32 v52, v52
	v_exp_f32_e32 v53, v53
	v_exp_f32_e32 v54, v54
	v_exp_f32_e32 v55, v55
	v_exp_f32_e32 v56, v56
	v_exp_f32_e32 v57, v57
	v_exp_f32_e32 v58, v58
	v_exp_f32_e32 v59, v59
	v_exp_f32_e32 v60, v60
	v_exp_f32_e32 v61, v61
	v_exp_f32_e32 v62, v62
	v_exp_f32_e32 v63, v63
	v_pk_add_f32 v[200:201], v[48:49], v[50:51]
	v_pk_add_f32 v[200:201], v[200:201], v[52:53]
	v_pk_add_f32 v[200:201], v[200:201], v[54:55]
	v_pk_add_f32 v[200:201], v[200:201], v[56:57]
	v_pk_add_f32 v[200:201], v[200:201], v[58:59]
	v_pk_add_f32 v[200:201], v[200:201], v[60:61]
	v_pk_add_f32 v[200:201], v[200:201], v[62:63]
	v_cvt_pk_bf16_f32 v48, v48, v49
	v_cvt_pk_bf16_f32 v49, v50, v51
	v_cvt_pk_bf16_f32 v50, v52, v53
	v_cvt_pk_bf16_f32 v51, v54, v55
	v_cvt_pk_bf16_f32 v52, v56, v57
	v_cvt_pk_bf16_f32 v53, v58, v59
	v_cvt_pk_bf16_f32 v54, v60, v61
	v_cvt_pk_bf16_f32 v55, v62, v63
	v_exp_f32_e32 v32, v32
	v_exp_f32_e32 v33, v33
	v_exp_f32_e32 v34, v34
	v_exp_f32_e32 v35, v35
	v_exp_f32_e32 v36, v36
	v_exp_f32_e32 v37, v37
	v_exp_f32_e32 v38, v38
	v_exp_f32_e32 v39, v39
	v_exp_f32_e32 v40, v40
	v_exp_f32_e32 v41, v41
	v_exp_f32_e32 v42, v42
	v_exp_f32_e32 v43, v43
	v_exp_f32_e32 v44, v44
	v_exp_f32_e32 v45, v45
	v_exp_f32_e32 v46, v46
	v_exp_f32_e32 v47, v47
	v_pk_add_f32 v[200:201], v[200:201], v[32:33]
	v_pk_add_f32 v[200:201], v[200:201], v[34:35]
	v_pk_add_f32 v[200:201], v[200:201], v[36:37]
	v_pk_add_f32 v[200:201], v[200:201], v[38:39]
	v_pk_add_f32 v[200:201], v[200:201], v[40:41]
	v_pk_add_f32 v[200:201], v[200:201], v[42:43]
	v_pk_add_f32 v[200:201], v[200:201], v[44:45]
	v_pk_add_f32 v[200:201], v[200:201], v[46:47]
	v_cvt_pk_bf16_f32 v32, v32, v33
	v_cvt_pk_bf16_f32 v33, v34, v35
	v_cvt_pk_bf16_f32 v34, v36, v37
	v_cvt_pk_bf16_f32 v35, v38, v39
	v_cvt_pk_bf16_f32 v36, v40, v41
	v_cvt_pk_bf16_f32 v37, v42, v43
	v_cvt_pk_bf16_f32 v38, v44, v45
	v_cvt_pk_bf16_f32 v39, v46, v47
	v_add_f32_e32 v201, v200, v201
	v_add_f32_e32 v213, v213, v201
	v_lshl_add_u64 v[166:167], v[166:167], 0, s[24:25]
	v_lshl_add_u64 v[168:169], v[168:169], 0, s[24:25]
	v_lshl_add_u64 v[170:171], v[170:171], 0, s[30:31]
	v_lshl_add_u64 v[172:173], v[172:173], 0, s[30:31]
	v_lshl_add_u64 v[174:175], v[174:175], 0, s[30:31]
	ds_read_b128 v[214:217], v210 offset:0
	ds_read_b128 v[234:237], v210 offset:32
	ds_read_b128 v[238:241], v210 offset:64
	ds_read_b128 v[242:245], v210 offset:96
	ds_read_b128 v[40:43], v210 offset:128
	ds_read_b128 v[44:47], v210 offset:160
	s_barrier
	s_and_b64 vcc, exec, s[26:27]
	s_cbranch_vccnz .Lpq0_exit
	s_mov_b32 s4, s15
	s_branch .LBB0_795
